# k19 + gate tiles (P4c stores / P7 loads 1 KiB contiguous) + leading-half align barrier moved to before the first full vmcnt wait in 8 epilogues
# speedup vs baseline: 1.0065x; 1.0026x over previous
.LBB0_613:
	s_lshl_b32 s100, s48, 5
	s_add_i32 s100, s100, s67
	s_lshl_b32 s100, s100, 3
	s_mov_b32 s101, 0x9000
	v_lshrrev_b32_e32 v224, 6, v0
	v_and_b32_e32 v225, 63, v0
	v_add_u32_e32 v224, s100, v224
	v_mul_lo_u32 v224, v224, s101
	v_lshl_add_u32 v224, v225, 4, v224
	v_mov_b32_e32 v225, 0
	v_lshl_add_u64 v[224:225], s[16:17], 0, v[224:225]
	s_mov_b32 s101, 0
	v_lshl_or_b32 v156, s67, 8, v162
	v_ashrrev_i32_e32 v157, 31, v156
	v_lshl_add_u32 v152, s48, 8, v1
	v_lshl_add_u64 v[150:151], v[156:157], 2, s[18:19]
	v_ashrrev_i32_e32 v153, 31, v152
	global_load_dwordx4 v[166:169], v[150:151], off offset:16
	global_load_dwordx4 v[158:161], v[150:151], off
	v_lshl_add_u64 v[148:149], v[152:153], 2, s[26:27]
	global_load_dword v153, v[148:149], off
	global_load_dword v190, v[148:149], off
	global_load_dword v192, v[148:149], off offset:64
	global_load_dword v194, v[148:149], off offset:128
	global_load_dword v196, v[148:149], off offset:192
	global_load_dword v198, v[148:149], off offset:512
	global_load_dword v200, v[148:149], off offset:576
	global_load_dword v202, v[148:149], off offset:640
	global_load_dword v204, v[148:149], off offset:704
	global_load_dwordx4 v[206:209], v[150:151], off offset:512
	global_load_dwordx4 v[210:213], v[150:151], off offset:528
	v_cvt_f32_i32_e32 v172, v126
	v_cvt_f32_i32_e32 v173, v127
	v_cvt_f32_i32_e32 v174, v128
	v_cvt_f32_i32_e32 v175, v129
	v_cvt_f32_i32_e32 v176, v122
	v_cvt_f32_i32_e32 v177, v123
	v_cvt_f32_i32_e32 v178, v124
	v_cvt_f32_i32_e32 v179, v125
	v_or_b32_e32 v170, 16, v152
	v_lshlrev_b64 v[128:129], 1, v[156:157]
	v_ashrrev_i32_e32 v171, 31, v170
	v_lshl_add_u64 v[124:125], v[170:171], 2, s[26:27]
	s_cmp_lt_i32 s67, 0
	v_mov_b64_e32 v[154:155], s[16:17]
	s_movk_i32 s100, 0x0
	v_lshl_add_u64 v[122:123], v[224:225], 0, s[100:101]
	s_cselect_b64 s[6:7], -1, 0
	s_nop 0
	v_cvt_f32_i32_e32 v118, v118
	v_cvt_f32_i32_e32 v119, v119
	v_cvt_f32_i32_e32 v120, v120
	v_cvt_f32_i32_e32 v121, v121
	v_cvt_f32_i32_e32 v110, v110
	v_cvt_f32_i32_e32 v111, v111
	v_cvt_f32_i32_e32 v112, v112
	v_cvt_f32_i32_e32 v113, v113
	v_cvt_f32_i32_e32 v102, v102
	v_cvt_f32_i32_e32 v103, v103
	v_cvt_f32_i32_e32 v104, v104
	v_cvt_f32_i32_e32 v105, v105
	v_cvt_f32_i32_e32 v100, v100
	v_cvt_f32_i32_e32 v101, v101
	v_cvt_f32_i32_e32 v94, v94
	v_cvt_f32_i32_e32 v95, v95
	v_cvt_f32_i32_e32 v96, v96
	v_cvt_f32_i32_e32 v97, v97
	v_cvt_f32_i32_e32 v92, v92
	v_cvt_f32_i32_e32 v93, v93
	v_cvt_f32_i32_e32 v86, v86
	v_cvt_f32_i32_e32 v87, v87
	v_cvt_f32_i32_e32 v88, v88
	v_cvt_f32_i32_e32 v89, v89
	v_cvt_f32_i32_e32 v84, v84
	v_cvt_f32_i32_e32 v85, v85
	v_cvt_f32_i32_e32 v78, v78
	v_cvt_f32_i32_e32 v79, v79
	v_cvt_f32_i32_e32 v80, v80
	v_cvt_f32_i32_e32 v81, v81
	v_cvt_f32_i32_e32 v76, v76
	v_cvt_f32_i32_e32 v77, v77
	v_cvt_f32_i32_e32 v70, v70
	v_cvt_f32_i32_e32 v71, v71
	v_cvt_f32_i32_e32 v72, v72
	v_cvt_f32_i32_e32 v73, v73
	v_cvt_f32_i32_e32 v68, v68
	v_cvt_f32_i32_e32 v69, v69
	v_cvt_f32_i32_e32 v53, v53
	v_cvt_f32_i32_e32 v54, v54
	v_cvt_f32_i32_e32 v55, v55
	v_cvt_f32_i32_e32 v56, v56
	v_cvt_f32_i32_e32 v57, v57
	v_cvt_f32_i32_e32 v50, v50
	v_cvt_f32_i32_e32 v51, v51
	v_cvt_f32_i32_e32 v52, v52
	v_cvt_f32_i32_e32 v45, v45
	v_cvt_f32_i32_e32 v46, v46
	v_cvt_f32_i32_e32 v47, v47
	v_cvt_f32_i32_e32 v48, v48
	v_cvt_f32_i32_e32 v49, v49
	v_cvt_f32_i32_e32 v42, v42
	v_cvt_f32_i32_e32 v43, v43
	v_cvt_f32_i32_e32 v44, v44
	v_cvt_f32_i32_e32 v37, v37
	v_cvt_f32_i32_e32 v38, v38
	v_cvt_f32_i32_e32 v39, v39
	v_cvt_f32_i32_e32 v40, v40
	s_cmp_lg_u64 s[24:25], 0
	s_cbranch_scc0 .Lalb_5
	s_barrier
.Lalb_5:
	s_waitcnt vmcnt(0)
	s_mov_b32 s98, 0x3c3a1e78
	v_pk_mul_f32 v[126:127], v[168:169], s[98:99] op_sel_hi:[1,0]
	v_pk_mul_f32 v[156:157], v[160:161], s[98:99] op_sel_hi:[1,0]
	v_pk_mul_f32 v[160:161], v[158:159], s[98:99] op_sel_hi:[1,0]
	v_pk_mul_f32 v[158:159], v[166:167], s[98:99] op_sel_hi:[1,0]
	v_mul_f32_e32 v166, v160, v153
	v_mul_f32_e32 v167, v161, v153
	v_mul_f32_e32 v168, v156, v153
	v_mul_f32_e32 v169, v157, v153
	v_mul_f32_e32 v171, v153, v158
	v_mul_f32_e32 v180, v153, v159
	v_mul_f32_e32 v181, v153, v126
	v_mul_f32_e32 v153, v153, v127
	v_mul_f32_e32 v166, v166, v172
	v_mul_f32_e32 v167, v167, v173
	v_mul_f32_e32 v168, v168, v174
	v_mul_f32_e32 v169, v169, v175
	v_mul_f32_e32 v171, v171, v176
	v_mul_f32_e32 v172, v180, v177
	v_mul_f32_e32 v173, v181, v178
	v_mul_f32_e32 v153, v153, v179
	v_exp_f32_e64 v174, -v166
	v_exp_f32_e64 v175, -v167
	v_exp_f32_e64 v176, -v168
	v_exp_f32_e64 v177, -v169
	v_exp_f32_e64 v178, -v171
	v_exp_f32_e64 v179, -v172
	v_exp_f32_e64 v180, -v173
	v_exp_f32_e64 v181, -v153
	v_add_f32_e32 v174, 1.0, v174
	v_add_f32_e32 v175, 1.0, v175
	v_add_f32_e32 v176, 1.0, v176
	v_add_f32_e32 v177, 1.0, v177
	v_add_f32_e32 v178, 1.0, v178
	v_add_f32_e32 v179, 1.0, v179
	v_add_f32_e32 v180, 1.0, v180
	v_add_f32_e32 v181, 1.0, v181
	v_rcp_f32_e32 v174, v174
	v_rcp_f32_e32 v175, v175
	v_rcp_f32_e32 v176, v176
	v_rcp_f32_e32 v177, v177
	v_rcp_f32_e32 v178, v178
	v_rcp_f32_e32 v179, v179
	v_rcp_f32_e32 v180, v180
	v_rcp_f32_e32 v181, v181
	v_cvt_pk_bf16_f32 v166, v174, v175
	v_cvt_pk_bf16_f32 v167, v176, v177
	v_cvt_pk_bf16_f32 v168, v178, v179
	v_cvt_pk_bf16_f32 v169, v180, v181
	global_store_dwordx4 v[122:123], v[166:169], off
	s_nop 1
	v_cvt_f32_i32_e32 v171, v116
	v_cvt_f32_i32_e32 v168, v114
	v_cvt_f32_i32_e32 v169, v115
	v_cvt_f32_i32_e32 v172, v117
	v_or_b32_e32 v166, 32, v152
	v_ashrrev_i32_e32 v167, 31, v166
	s_movk_i32 s100, 0x800
	v_lshl_add_u64 v[114:115], v[224:225], 0, s[100:101]
	v_lshl_add_u64 v[116:117], v[166:167], 2, s[26:27]
	s_nop 0
	v_cvt_f32_i32_e32 v41, v41
	v_cvt_f32_i32_e32 v34, v34
	v_cvt_f32_i32_e32 v35, v35
	v_cvt_f32_i32_e32 v36, v36
	v_cvt_f32_i32_e32 v29, v29
	v_cvt_f32_i32_e32 v30, v30
	v_cvt_f32_i32_e32 v31, v31
	v_cvt_f32_i32_e32 v32, v32
	v_cvt_f32_i32_e32 v33, v33
	v_cvt_f32_i32_e32 v26, v26
	v_cvt_f32_i32_e32 v27, v27
	v_cvt_f32_i32_e32 v28, v28
	v_cvt_f32_i32_e32 v21, v21
	v_cvt_f32_i32_e32 v22, v22
	v_cvt_f32_i32_e32 v23, v23
	v_cvt_f32_i32_e32 v24, v24
	v_cvt_f32_i32_e32 v25, v25
	v_cvt_f32_i32_e32 v18, v18
	v_cvt_f32_i32_e32 v19, v19
	v_cvt_f32_i32_e32 v20, v20
	v_cvt_f32_i32_e32 v13, v13
	v_cvt_f32_i32_e32 v14, v14
	v_cvt_f32_i32_e32 v15, v15
	v_cvt_f32_i32_e32 v16, v16
	v_cvt_f32_i32_e32 v17, v17
	v_cvt_f32_i32_e32 v10, v10
	v_cvt_f32_i32_e32 v11, v11
	v_cvt_f32_i32_e32 v12, v12
	v_cvt_f32_i32_e32 v5, v5
	v_cvt_f32_i32_e32 v6, v6
	v_cvt_f32_i32_e32 v7, v7
	v_cvt_f32_i32_e32 v8, v8
	v_cvt_f32_i32_e32 v9, v9
	v_cvt_f32_i32_e32 v2, v2
	v_cvt_f32_i32_e32 v3, v3
	v_cvt_f32_i32_e32 v4, v4
	s_and_b64 vcc, exec, s[4:5]
	v_mov_b32_e32 v153, v192
	v_mul_f32_e32 v167, v160, v153
	v_mul_f32_e32 v170, v161, v153
	v_mul_f32_e32 v173, v156, v153
	v_mul_f32_e32 v174, v157, v153
	v_mul_f32_e32 v175, v158, v153
	v_mul_f32_e32 v176, v159, v153
	v_mul_f32_e32 v177, v126, v153
	v_mul_f32_e32 v153, v127, v153
	v_mul_f32_e32 v118, v167, v118
	v_mul_f32_e32 v119, v170, v119
	v_mul_f32_e32 v120, v173, v120
	v_mul_f32_e32 v121, v174, v121
	v_mul_f32_e32 v167, v175, v168
	v_mul_f32_e32 v168, v176, v169
	v_mul_f32_e32 v169, v177, v171
	v_mul_f32_e32 v153, v153, v172
	v_exp_f32_e64 v170, -v118
	v_exp_f32_e64 v171, -v119
	v_exp_f32_e64 v172, -v120
	v_exp_f32_e64 v173, -v121
	v_exp_f32_e64 v174, -v167
	v_exp_f32_e64 v175, -v168
	v_exp_f32_e64 v176, -v169
	v_exp_f32_e64 v177, -v153
	v_add_f32_e32 v170, 1.0, v170
	v_add_f32_e32 v171, 1.0, v171
	v_add_f32_e32 v172, 1.0, v172
	v_add_f32_e32 v173, 1.0, v173
	v_add_f32_e32 v174, 1.0, v174
	v_add_f32_e32 v175, 1.0, v175
	v_add_f32_e32 v176, 1.0, v176
	v_add_f32_e32 v177, 1.0, v177
	v_rcp_f32_e32 v170, v170
	v_rcp_f32_e32 v171, v171
	v_rcp_f32_e32 v172, v172
	v_rcp_f32_e32 v173, v173
	v_rcp_f32_e32 v174, v174
	v_rcp_f32_e32 v175, v175
	v_rcp_f32_e32 v176, v176
	v_rcp_f32_e32 v177, v177
	v_cvt_pk_bf16_f32 v118, v170, v171
	v_cvt_pk_bf16_f32 v119, v172, v173
	v_cvt_pk_bf16_f32 v120, v174, v175
	v_cvt_pk_bf16_f32 v121, v176, v177
	global_store_dwordx4 v[114:115], v[118:121], off
	s_nop 1
	v_cvt_f32_i32_e32 v153, v107
	v_cvt_f32_i32_e32 v121, v106
	v_cvt_f32_i32_e32 v167, v108
	v_cvt_f32_i32_e32 v168, v109
	v_or_b32_e32 v118, 48, v152
	v_ashrrev_i32_e32 v119, 31, v118
	s_movk_i32 s100, 0x1000
	v_lshl_add_u64 v[106:107], v[224:225], 0, s[100:101]
	v_lshl_add_u64 v[108:109], v[118:119], 2, s[26:27]
	s_nop 0
	v_mov_b32_e32 v120, v194
	v_mul_f32_e32 v119, v160, v120
	v_mul_f32_e32 v166, v161, v120
	v_mul_f32_e32 v169, v156, v120
	v_mul_f32_e32 v170, v157, v120
	v_mul_f32_e32 v171, v158, v120
	v_mul_f32_e32 v172, v159, v120
	v_mul_f32_e32 v173, v126, v120
	v_mul_f32_e32 v120, v127, v120
	v_mul_f32_e32 v110, v119, v110
	v_mul_f32_e32 v111, v166, v111
	v_mul_f32_e32 v112, v169, v112
	v_mul_f32_e32 v113, v170, v113
	v_mul_f32_e32 v119, v171, v121
	v_mul_f32_e32 v121, v172, v153
	v_mul_f32_e32 v153, v173, v167
	v_mul_f32_e32 v120, v120, v168
	v_exp_f32_e64 v166, -v110
	v_exp_f32_e64 v167, -v111
	v_exp_f32_e64 v168, -v112
	v_exp_f32_e64 v169, -v113
	v_exp_f32_e64 v170, -v119
	v_exp_f32_e64 v171, -v121
	v_exp_f32_e64 v172, -v153
	v_exp_f32_e64 v173, -v120
	v_add_f32_e32 v166, 1.0, v166
	v_add_f32_e32 v167, 1.0, v167
	v_add_f32_e32 v168, 1.0, v168
	v_add_f32_e32 v169, 1.0, v169
	v_add_f32_e32 v170, 1.0, v170
	v_add_f32_e32 v171, 1.0, v171
	v_add_f32_e32 v172, 1.0, v172
	v_add_f32_e32 v173, 1.0, v173
	v_rcp_f32_e32 v166, v166
	v_rcp_f32_e32 v167, v167
	v_rcp_f32_e32 v168, v168
	v_rcp_f32_e32 v169, v169
	v_rcp_f32_e32 v170, v170
	v_rcp_f32_e32 v171, v171
	v_rcp_f32_e32 v172, v172
	v_rcp_f32_e32 v173, v173
	v_cvt_pk_bf16_f32 v110, v166, v167
	v_cvt_pk_bf16_f32 v111, v168, v169
	v_cvt_pk_bf16_f32 v112, v170, v171
	v_cvt_pk_bf16_f32 v113, v172, v173
	global_store_dwordx4 v[106:107], v[110:113], off
	s_nop 1
	v_mov_b32_e32 v110, v196
	v_mul_f32_e32 v119, v156, v110
	v_cvt_f32_i32_e32 v111, v98
	v_cvt_f32_i32_e32 v112, v99
	s_movk_i32 s100, 0x1800
	v_lshl_add_u64 v[98:99], v[224:225], 0, s[100:101]
	v_mul_f32_e32 v113, v160, v110
	v_mul_f32_e32 v118, v161, v110
	v_mul_f32_e32 v120, v157, v110
	v_mul_f32_e32 v121, v158, v110
	v_mul_f32_e32 v153, v159, v110
	v_mul_f32_e32 v166, v126, v110
	v_mul_f32_e32 v110, v127, v110
	v_mul_f32_e32 v102, v113, v102
	v_mul_f32_e32 v103, v118, v103
	v_mul_f32_e32 v104, v119, v104
	v_mul_f32_e32 v105, v120, v105
	v_mul_f32_e32 v111, v121, v111
	v_mul_f32_e32 v112, v153, v112
	v_mul_f32_e32 v100, v166, v100
	v_mul_f32_e32 v101, v110, v101
	v_exp_f32_e64 v110, -v102
	v_exp_f32_e64 v113, -v103
	v_exp_f32_e64 v118, -v104
	v_exp_f32_e64 v119, -v105
	v_exp_f32_e64 v120, -v111
	v_exp_f32_e64 v121, -v112
	v_exp_f32_e64 v153, -v100
	v_exp_f32_e64 v166, -v101
	v_add_f32_e32 v110, 1.0, v110
	v_add_f32_e32 v113, 1.0, v113
	v_add_f32_e32 v118, 1.0, v118
	v_add_f32_e32 v119, 1.0, v119
	v_add_f32_e32 v120, 1.0, v120
	v_add_f32_e32 v121, 1.0, v121
	v_add_f32_e32 v153, 1.0, v153
	v_add_f32_e32 v166, 1.0, v166
	v_rcp_f32_e32 v110, v110
	v_rcp_f32_e32 v113, v113
	v_rcp_f32_e32 v118, v118
	v_rcp_f32_e32 v119, v119
	v_rcp_f32_e32 v120, v120
	v_rcp_f32_e32 v121, v121
	v_rcp_f32_e32 v153, v153
	v_rcp_f32_e32 v166, v166
	s_nop 0
	v_cvt_pk_bf16_f32 v100, v110, v113
	v_cvt_pk_bf16_f32 v101, v118, v119
	v_cvt_pk_bf16_f32 v102, v120, v121
	v_cvt_pk_bf16_f32 v103, v153, v166
	global_store_dwordx4 v[98:99], v[100:103], off
	s_nop 1
	v_mov_b32_e32 v100, v198
	v_mul_f32_e32 v104, v161, v100
	v_cvt_f32_i32_e32 v101, v90
	v_cvt_f32_i32_e32 v102, v91
	v_mul_f32_e32 v103, v160, v100
	v_mul_f32_e32 v105, v156, v100
	v_mul_f32_e32 v110, v157, v100
	v_mul_f32_e32 v111, v158, v100
	v_mul_f32_e32 v112, v159, v100
	v_mul_f32_e32 v113, v126, v100
	v_mul_f32_e32 v100, v127, v100
	v_mul_f32_e32 v94, v103, v94
	v_mul_f32_e32 v95, v104, v95
	v_mul_f32_e32 v96, v105, v96
	v_mul_f32_e32 v97, v110, v97
	v_mul_f32_e32 v101, v111, v101
	v_mul_f32_e32 v102, v112, v102
	v_mul_f32_e32 v92, v113, v92
	v_mul_f32_e32 v93, v100, v93
	v_exp_f32_e64 v100, -v94
	v_exp_f32_e64 v103, -v95
	v_exp_f32_e64 v104, -v96
	v_exp_f32_e64 v105, -v97
	v_exp_f32_e64 v110, -v101
	v_exp_f32_e64 v111, -v102
	v_exp_f32_e64 v112, -v92
	v_exp_f32_e64 v113, -v93
	v_add_f32_e32 v100, 1.0, v100
	v_add_f32_e32 v103, 1.0, v103
	v_add_f32_e32 v104, 1.0, v104
	v_add_f32_e32 v105, 1.0, v105
	v_add_f32_e32 v110, 1.0, v110
	v_add_f32_e32 v111, 1.0, v111
	v_add_f32_e32 v112, 1.0, v112
	v_add_f32_e32 v113, 1.0, v113
	v_rcp_f32_e32 v100, v100
	v_rcp_f32_e32 v103, v103
	v_rcp_f32_e32 v104, v104
	v_rcp_f32_e32 v105, v105
	v_rcp_f32_e32 v110, v110
	v_rcp_f32_e32 v111, v111
	v_rcp_f32_e32 v112, v112
	v_rcp_f32_e32 v113, v113
	v_add_u32_e32 v90, 0x80, v152
	s_movk_i32 s100, 0x2000
	v_lshl_add_u64 v[90:91], v[224:225], 0, s[100:101]
	s_nop 0
	v_cvt_pk_bf16_f32 v92, v100, v103
	v_cvt_pk_bf16_f32 v93, v104, v105
	v_cvt_pk_bf16_f32 v94, v110, v111
	v_cvt_pk_bf16_f32 v95, v112, v113
	global_store_dwordx4 v[90:91], v[92:95], off
	s_nop 1
	v_mov_b32_e32 v92, v200
	v_mul_f32_e32 v96, v161, v92
	v_cvt_f32_i32_e32 v93, v82
	v_cvt_f32_i32_e32 v94, v83
	v_mul_f32_e32 v95, v160, v92
	v_mul_f32_e32 v97, v156, v92
	v_mul_f32_e32 v100, v157, v92
	v_mul_f32_e32 v101, v158, v92
	v_mul_f32_e32 v102, v159, v92
	v_mul_f32_e32 v103, v126, v92
	v_mul_f32_e32 v92, v127, v92
	v_mul_f32_e32 v86, v95, v86
	v_mul_f32_e32 v87, v96, v87
	v_mul_f32_e32 v88, v97, v88
	v_mul_f32_e32 v89, v100, v89
	v_mul_f32_e32 v93, v101, v93
	v_mul_f32_e32 v94, v102, v94
	v_mul_f32_e32 v84, v103, v84
	v_mul_f32_e32 v85, v92, v85
	v_exp_f32_e64 v92, -v86
	v_exp_f32_e64 v95, -v87
	v_exp_f32_e64 v96, -v88
	v_exp_f32_e64 v97, -v89
	v_exp_f32_e64 v100, -v93
	v_exp_f32_e64 v101, -v94
	v_exp_f32_e64 v102, -v84
	v_exp_f32_e64 v103, -v85
	v_add_f32_e32 v92, 1.0, v92
	v_add_f32_e32 v95, 1.0, v95
	v_add_f32_e32 v96, 1.0, v96
	v_add_f32_e32 v97, 1.0, v97
	v_add_f32_e32 v100, 1.0, v100
	v_add_f32_e32 v101, 1.0, v101
	v_add_f32_e32 v102, 1.0, v102
	v_add_f32_e32 v103, 1.0, v103
	v_rcp_f32_e32 v92, v92
	v_rcp_f32_e32 v95, v95
	v_rcp_f32_e32 v96, v96
	v_rcp_f32_e32 v97, v97
	v_rcp_f32_e32 v100, v100
	v_rcp_f32_e32 v101, v101
	v_rcp_f32_e32 v102, v102
	v_rcp_f32_e32 v103, v103
	v_add_u32_e32 v82, 0x90, v152
	s_movk_i32 s100, 0x2800
	v_lshl_add_u64 v[82:83], v[224:225], 0, s[100:101]
	s_nop 0
	v_cvt_pk_bf16_f32 v84, v92, v95
	v_cvt_pk_bf16_f32 v85, v96, v97
	v_cvt_pk_bf16_f32 v86, v100, v101
	v_cvt_pk_bf16_f32 v87, v102, v103
	global_store_dwordx4 v[82:83], v[84:87], off
	s_nop 1
	v_mov_b32_e32 v84, v202
	v_mul_f32_e32 v88, v161, v84
	v_cvt_f32_i32_e32 v85, v74
	v_cvt_f32_i32_e32 v86, v75
	v_mul_f32_e32 v87, v160, v84
	v_mul_f32_e32 v89, v156, v84
	v_mul_f32_e32 v92, v157, v84
	v_mul_f32_e32 v93, v158, v84
	v_mul_f32_e32 v94, v159, v84
	v_mul_f32_e32 v95, v126, v84
	v_mul_f32_e32 v84, v127, v84
	v_mul_f32_e32 v78, v87, v78
	v_mul_f32_e32 v79, v88, v79
	v_mul_f32_e32 v80, v89, v80
	v_mul_f32_e32 v81, v92, v81
	v_mul_f32_e32 v85, v93, v85
	v_mul_f32_e32 v86, v94, v86
	v_mul_f32_e32 v76, v95, v76
	v_mul_f32_e32 v77, v84, v77
	v_exp_f32_e64 v84, -v78
	v_exp_f32_e64 v87, -v79
	v_exp_f32_e64 v88, -v80
	v_exp_f32_e64 v89, -v81
	v_exp_f32_e64 v92, -v85
	v_exp_f32_e64 v93, -v86
	v_exp_f32_e64 v94, -v76
	v_exp_f32_e64 v95, -v77
	v_add_f32_e32 v84, 1.0, v84
	v_add_f32_e32 v87, 1.0, v87
	v_add_f32_e32 v88, 1.0, v88
	v_add_f32_e32 v89, 1.0, v89
	v_add_f32_e32 v92, 1.0, v92
	v_add_f32_e32 v93, 1.0, v93
	v_add_f32_e32 v94, 1.0, v94
	v_add_f32_e32 v95, 1.0, v95
	v_rcp_f32_e32 v84, v84
	v_rcp_f32_e32 v87, v87
	v_rcp_f32_e32 v88, v88
	v_rcp_f32_e32 v89, v89
	v_rcp_f32_e32 v92, v92
	v_rcp_f32_e32 v93, v93
	v_rcp_f32_e32 v94, v94
	v_rcp_f32_e32 v95, v95
	v_add_u32_e32 v74, 0xa0, v152
	s_movk_i32 s100, 0x3000
	v_lshl_add_u64 v[74:75], v[224:225], 0, s[100:101]
	s_nop 0
	v_cvt_pk_bf16_f32 v76, v84, v87
	v_cvt_pk_bf16_f32 v77, v88, v89
	v_cvt_pk_bf16_f32 v78, v92, v93
	v_cvt_pk_bf16_f32 v79, v94, v95
	global_store_dwordx4 v[74:75], v[76:79], off
	s_nop 1
	v_cvt_f32_i32_e32 v88, v61
	v_cvt_f32_i32_e32 v77, v66
	v_cvt_f32_i32_e32 v78, v67
	v_add_u32_e32 v66, 0xb0, v152
	s_movk_i32 s100, 0x3800
	v_lshl_add_u64 v[66:67], v[224:225], 0, s[100:101]
	s_nop 0
	s_mov_b64 s[0:1], -1
	v_mov_b32_e32 v76, v204
	v_mul_f32_e32 v79, v160, v76
	v_mul_f32_e32 v80, v161, v76
	v_mul_f32_e32 v81, v156, v76
	v_mul_f32_e32 v84, v157, v76
	v_mul_f32_e32 v85, v158, v76
	v_mul_f32_e32 v86, v159, v76
	v_mul_f32_e32 v87, v126, v76
	v_mul_f32_e32 v76, v127, v76
	v_mul_f32_e32 v70, v79, v70
	v_mul_f32_e32 v71, v80, v71
	v_mul_f32_e32 v72, v81, v72
	v_mul_f32_e32 v73, v84, v73
	v_mul_f32_e32 v77, v85, v77
	v_mul_f32_e32 v78, v86, v78
	v_mul_f32_e32 v68, v87, v68
	v_mul_f32_e32 v69, v76, v69
	v_exp_f32_e64 v76, -v70
	v_exp_f32_e64 v79, -v71
	v_exp_f32_e64 v80, -v72
	v_exp_f32_e64 v81, -v73
	v_exp_f32_e64 v84, -v77
	v_exp_f32_e64 v85, -v78
	v_exp_f32_e64 v86, -v68
	v_exp_f32_e64 v87, -v69
	v_add_f32_e32 v76, 1.0, v76
	v_add_f32_e32 v79, 1.0, v79
	v_add_f32_e32 v80, 1.0, v80
	v_add_f32_e32 v81, 1.0, v81
	v_add_f32_e32 v84, 1.0, v84
	v_add_f32_e32 v85, 1.0, v85
	v_add_f32_e32 v86, 1.0, v86
	v_add_f32_e32 v87, 1.0, v87
	v_rcp_f32_e32 v76, v76
	v_rcp_f32_e32 v79, v79
	v_rcp_f32_e32 v80, v80
	v_rcp_f32_e32 v81, v81
	v_rcp_f32_e32 v84, v84
	v_rcp_f32_e32 v85, v85
	v_rcp_f32_e32 v86, v86
	v_rcp_f32_e32 v87, v87
	v_cvt_pk_bf16_f32 v68, v76, v79
	v_cvt_pk_bf16_f32 v69, v80, v81
	v_cvt_pk_bf16_f32 v70, v84, v85
	v_cvt_pk_bf16_f32 v71, v86, v87
	global_store_dwordx4 v[66:67], v[68:71], off
	s_nop 1
	s_nop 1
	v_cvt_f32_i32_e32 v73, v62
	v_cvt_f32_i32_e32 v80, v63
	v_cvt_f32_i32_e32 v81, v64
	v_cvt_f32_i32_e32 v84, v65
	v_cvt_f32_i32_e32 v85, v58
	v_cvt_f32_i32_e32 v86, v59
	v_cvt_f32_i32_e32 v87, v60
	v_pk_mul_f32 v[60:61], v[208:209], s[98:99] op_sel_hi:[1,0]
	v_pk_mul_f32 v[64:65], v[206:207], s[98:99] op_sel_hi:[1,0]
	v_pk_mul_f32 v[58:59], v[212:213], s[98:99] op_sel_hi:[1,0]
	v_pk_mul_f32 v[62:63], v[210:211], s[98:99] op_sel_hi:[1,0]
	v_mov_b32_e32 v72, v190
	v_mul_f32_e32 v68, v64, v72
	v_mul_f32_e32 v69, v65, v72
	v_mul_f32_e32 v70, v60, v72
	v_mul_f32_e32 v71, v61, v72
	v_mul_f32_e32 v76, v72, v62
	v_mul_f32_e32 v77, v72, v63
	v_mul_f32_e32 v78, v72, v58
	v_mul_f32_e32 v72, v72, v59
	v_mul_f32_e32 v68, v68, v73
	v_mul_f32_e32 v69, v69, v80
	v_mul_f32_e32 v70, v70, v81
	v_mul_f32_e32 v71, v71, v84
	v_mul_f32_e32 v73, v76, v85
	v_mul_f32_e32 v76, v77, v86
	v_mul_f32_e32 v77, v78, v87
	v_mul_f32_e32 v72, v72, v88
	v_exp_f32_e64 v78, -v68
	v_exp_f32_e64 v79, -v69
	v_exp_f32_e64 v80, -v70
	v_exp_f32_e64 v81, -v71
	v_exp_f32_e64 v84, -v73
	v_exp_f32_e64 v85, -v76
	v_exp_f32_e64 v86, -v77
	v_exp_f32_e64 v87, -v72
	v_add_f32_e32 v78, 1.0, v78
	v_add_f32_e32 v79, 1.0, v79
	v_add_f32_e32 v80, 1.0, v80
	v_add_f32_e32 v81, 1.0, v81
	v_add_f32_e32 v84, 1.0, v84
	v_add_f32_e32 v85, 1.0, v85
	v_add_f32_e32 v86, 1.0, v86
	v_add_f32_e32 v87, 1.0, v87
	v_rcp_f32_e32 v78, v78
	v_rcp_f32_e32 v79, v79
	v_rcp_f32_e32 v80, v80
	v_rcp_f32_e32 v81, v81
	v_rcp_f32_e32 v84, v84
	v_rcp_f32_e32 v85, v85
	v_rcp_f32_e32 v86, v86
	v_rcp_f32_e32 v87, v87
	v_cvt_pk_bf16_f32 v68, v78, v79
	v_cvt_pk_bf16_f32 v69, v80, v81
	v_cvt_pk_bf16_f32 v70, v84, v85
	v_cvt_pk_bf16_f32 v71, v86, v87
	global_store_dwordx4 v[122:123], v[68:71], off offset:1024
	s_nop 1
	v_mov_b32_e32 v68, v192
	v_mul_f32_e32 v72, v61, v68
	v_mul_f32_e32 v69, v64, v68
	v_mul_f32_e32 v70, v65, v68
	v_mul_f32_e32 v71, v60, v68
	v_mul_f32_e32 v73, v62, v68
	v_mul_f32_e32 v76, v63, v68
	v_mul_f32_e32 v77, v58, v68
	v_mul_f32_e32 v68, v59, v68
	v_mul_f32_e32 v53, v68, v53
	v_mul_f32_e32 v54, v69, v54
	v_mul_f32_e32 v55, v70, v55
	v_mul_f32_e32 v56, v71, v56
	v_mul_f32_e32 v57, v72, v57
	v_mul_f32_e32 v50, v73, v50
	v_mul_f32_e32 v51, v76, v51
	v_mul_f32_e32 v52, v77, v52
	v_exp_f32_e64 v77, -v53
	v_exp_f32_e64 v68, -v54
	v_exp_f32_e64 v69, -v55
	v_exp_f32_e64 v70, -v56
	v_exp_f32_e64 v71, -v57
	v_exp_f32_e64 v72, -v50
	v_exp_f32_e64 v73, -v51
	v_exp_f32_e64 v76, -v52
	v_add_f32_e32 v77, 1.0, v77
	v_add_f32_e32 v68, 1.0, v68
	v_add_f32_e32 v69, 1.0, v69
	v_add_f32_e32 v70, 1.0, v70
	v_add_f32_e32 v71, 1.0, v71
	v_add_f32_e32 v72, 1.0, v72
	v_add_f32_e32 v73, 1.0, v73
	v_add_f32_e32 v76, 1.0, v76
	v_rcp_f32_e32 v77, v77
	v_rcp_f32_e32 v68, v68
	v_rcp_f32_e32 v69, v69
	v_rcp_f32_e32 v70, v70
	v_rcp_f32_e32 v71, v71
	v_rcp_f32_e32 v72, v72
	v_rcp_f32_e32 v73, v73
	v_rcp_f32_e32 v76, v76
	v_cvt_pk_bf16_f32 v50, v68, v69
	v_cvt_pk_bf16_f32 v51, v70, v71
	v_cvt_pk_bf16_f32 v52, v72, v73
	v_cvt_pk_bf16_f32 v53, v76, v77
	global_store_dwordx4 v[114:115], v[50:53], off offset:1024
	s_nop 1
	v_mov_b32_e32 v50, v194
	v_mul_f32_e32 v54, v61, v50
	v_mul_f32_e32 v51, v64, v50
	v_mul_f32_e32 v52, v65, v50
	v_mul_f32_e32 v53, v60, v50
	v_mul_f32_e32 v55, v62, v50
	v_mul_f32_e32 v56, v63, v50
	v_mul_f32_e32 v57, v58, v50
	v_mul_f32_e32 v50, v59, v50
	v_mul_f32_e32 v45, v50, v45
	v_mul_f32_e32 v46, v51, v46
	v_mul_f32_e32 v47, v52, v47
	v_mul_f32_e32 v48, v53, v48
	v_mul_f32_e32 v49, v54, v49
	v_mul_f32_e32 v42, v55, v42
	v_mul_f32_e32 v43, v56, v43
	v_mul_f32_e32 v44, v57, v44
	v_exp_f32_e64 v57, -v45
	v_exp_f32_e64 v50, -v46
	v_exp_f32_e64 v51, -v47
	v_exp_f32_e64 v52, -v48
	v_exp_f32_e64 v53, -v49
	v_exp_f32_e64 v54, -v42
	v_exp_f32_e64 v55, -v43
	v_exp_f32_e64 v56, -v44
	v_add_f32_e32 v57, 1.0, v57
	v_add_f32_e32 v50, 1.0, v50
	v_add_f32_e32 v51, 1.0, v51
	v_add_f32_e32 v52, 1.0, v52
	v_add_f32_e32 v53, 1.0, v53
	v_add_f32_e32 v54, 1.0, v54
	v_add_f32_e32 v55, 1.0, v55
	v_add_f32_e32 v56, 1.0, v56
	v_rcp_f32_e32 v57, v57
	v_rcp_f32_e32 v50, v50
	v_rcp_f32_e32 v51, v51
	v_rcp_f32_e32 v52, v52
	v_rcp_f32_e32 v53, v53
	v_rcp_f32_e32 v54, v54
	v_rcp_f32_e32 v55, v55
	v_rcp_f32_e32 v56, v56
	v_cvt_pk_bf16_f32 v42, v50, v51
	v_cvt_pk_bf16_f32 v43, v52, v53
	v_cvt_pk_bf16_f32 v44, v54, v55
	v_cvt_pk_bf16_f32 v45, v56, v57
	global_store_dwordx4 v[106:107], v[42:45], off offset:1024
	s_nop 1
	v_mov_b32_e32 v42, v196
	v_mul_f32_e32 v46, v61, v42
	v_mul_f32_e32 v43, v64, v42
	v_mul_f32_e32 v44, v65, v42
	v_mul_f32_e32 v45, v60, v42
	v_mul_f32_e32 v47, v62, v42
	v_mul_f32_e32 v48, v63, v42
	v_mul_f32_e32 v49, v58, v42
	v_mul_f32_e32 v42, v59, v42
	v_mul_f32_e32 v37, v42, v37
	v_mul_f32_e32 v38, v43, v38
	v_mul_f32_e32 v39, v44, v39
	v_mul_f32_e32 v40, v45, v40
	v_mul_f32_e32 v41, v46, v41
	v_mul_f32_e32 v34, v47, v34
	v_mul_f32_e32 v35, v48, v35
	v_mul_f32_e32 v36, v49, v36
	v_exp_f32_e64 v49, -v37
	v_exp_f32_e64 v42, -v38
	v_exp_f32_e64 v43, -v39
	v_exp_f32_e64 v44, -v40
	v_exp_f32_e64 v45, -v41
	v_exp_f32_e64 v46, -v34
	v_exp_f32_e64 v47, -v35
	v_exp_f32_e64 v48, -v36
	v_add_f32_e32 v49, 1.0, v49
	v_add_f32_e32 v42, 1.0, v42
	v_add_f32_e32 v43, 1.0, v43
	v_add_f32_e32 v44, 1.0, v44
	v_add_f32_e32 v45, 1.0, v45
	v_add_f32_e32 v46, 1.0, v46
	v_add_f32_e32 v47, 1.0, v47
	v_add_f32_e32 v48, 1.0, v48
	v_rcp_f32_e32 v49, v49
	v_rcp_f32_e32 v42, v42
	v_rcp_f32_e32 v43, v43
	v_rcp_f32_e32 v44, v44
	v_rcp_f32_e32 v45, v45
	v_rcp_f32_e32 v46, v46
	v_rcp_f32_e32 v47, v47
	v_rcp_f32_e32 v48, v48
	v_cvt_pk_bf16_f32 v34, v42, v43
	v_cvt_pk_bf16_f32 v35, v44, v45
	v_cvt_pk_bf16_f32 v36, v46, v47
	v_cvt_pk_bf16_f32 v37, v48, v49
	global_store_dwordx4 v[98:99], v[34:37], off offset:1024
	s_nop 1
	v_mov_b32_e32 v34, v198
	v_mul_f32_e32 v38, v61, v34
	v_mul_f32_e32 v35, v64, v34
	v_mul_f32_e32 v36, v65, v34
	v_mul_f32_e32 v37, v60, v34
	v_mul_f32_e32 v39, v62, v34
	v_mul_f32_e32 v40, v63, v34
	v_mul_f32_e32 v41, v58, v34
	v_mul_f32_e32 v34, v59, v34
	v_mul_f32_e32 v29, v34, v29
	v_mul_f32_e32 v30, v35, v30
	v_mul_f32_e32 v31, v36, v31
	v_mul_f32_e32 v32, v37, v32
	v_mul_f32_e32 v33, v38, v33
	v_mul_f32_e32 v26, v39, v26
	v_mul_f32_e32 v27, v40, v27
	v_mul_f32_e32 v28, v41, v28
	v_exp_f32_e64 v41, -v29
	v_exp_f32_e64 v34, -v30
	v_exp_f32_e64 v35, -v31
	v_exp_f32_e64 v36, -v32
	v_exp_f32_e64 v37, -v33
	v_exp_f32_e64 v38, -v26
	v_exp_f32_e64 v39, -v27
	v_exp_f32_e64 v40, -v28
	v_add_f32_e32 v41, 1.0, v41
	v_add_f32_e32 v34, 1.0, v34
	v_add_f32_e32 v35, 1.0, v35
	v_add_f32_e32 v36, 1.0, v36
	v_add_f32_e32 v37, 1.0, v37
	v_add_f32_e32 v38, 1.0, v38
	v_add_f32_e32 v39, 1.0, v39
	v_add_f32_e32 v40, 1.0, v40
	v_rcp_f32_e32 v41, v41
	v_rcp_f32_e32 v34, v34
	v_rcp_f32_e32 v35, v35
	v_rcp_f32_e32 v36, v36
	v_rcp_f32_e32 v37, v37
	v_rcp_f32_e32 v38, v38
	v_rcp_f32_e32 v39, v39
	v_rcp_f32_e32 v40, v40
	v_cvt_pk_bf16_f32 v26, v34, v35
	v_cvt_pk_bf16_f32 v27, v36, v37
	v_cvt_pk_bf16_f32 v28, v38, v39
	v_cvt_pk_bf16_f32 v29, v40, v41
	global_store_dwordx4 v[90:91], v[26:29], off offset:1024
	s_nop 1
	v_mov_b32_e32 v26, v200
	v_mul_f32_e32 v30, v61, v26
	v_mul_f32_e32 v27, v64, v26
	v_mul_f32_e32 v28, v65, v26
	v_mul_f32_e32 v29, v60, v26
	v_mul_f32_e32 v31, v62, v26
	v_mul_f32_e32 v32, v63, v26
	v_mul_f32_e32 v33, v58, v26
	v_mul_f32_e32 v26, v59, v26
	v_mul_f32_e32 v21, v26, v21
	v_mul_f32_e32 v22, v27, v22
	v_mul_f32_e32 v23, v28, v23
	v_mul_f32_e32 v24, v29, v24
	v_mul_f32_e32 v25, v30, v25
	v_mul_f32_e32 v18, v31, v18
	v_mul_f32_e32 v19, v32, v19
	v_mul_f32_e32 v20, v33, v20
	v_exp_f32_e64 v33, -v21
	v_exp_f32_e64 v26, -v22
	v_exp_f32_e64 v27, -v23
	v_exp_f32_e64 v28, -v24
	v_exp_f32_e64 v29, -v25
	v_exp_f32_e64 v30, -v18
	v_exp_f32_e64 v31, -v19
	v_exp_f32_e64 v32, -v20
	v_add_f32_e32 v33, 1.0, v33
	v_add_f32_e32 v26, 1.0, v26
	v_add_f32_e32 v27, 1.0, v27
	v_add_f32_e32 v28, 1.0, v28
	v_add_f32_e32 v29, 1.0, v29
	v_add_f32_e32 v30, 1.0, v30
	v_add_f32_e32 v31, 1.0, v31
	v_add_f32_e32 v32, 1.0, v32
	v_rcp_f32_e32 v33, v33
	v_rcp_f32_e32 v26, v26
	v_rcp_f32_e32 v27, v27
	v_rcp_f32_e32 v28, v28
	v_rcp_f32_e32 v29, v29
	v_rcp_f32_e32 v30, v30
	v_rcp_f32_e32 v31, v31
	v_rcp_f32_e32 v32, v32
	v_cvt_pk_bf16_f32 v18, v26, v27
	v_cvt_pk_bf16_f32 v19, v28, v29
	v_cvt_pk_bf16_f32 v20, v30, v31
	v_cvt_pk_bf16_f32 v21, v32, v33
	global_store_dwordx4 v[82:83], v[18:21], off offset:1024
	s_nop 1
	v_mov_b32_e32 v18, v202
	v_mul_f32_e32 v22, v61, v18
	v_mul_f32_e32 v19, v64, v18
	v_mul_f32_e32 v20, v65, v18
	v_mul_f32_e32 v21, v60, v18
	v_mul_f32_e32 v23, v62, v18
	v_mul_f32_e32 v24, v63, v18
	v_mul_f32_e32 v25, v58, v18
	v_mul_f32_e32 v18, v59, v18
	v_mul_f32_e32 v13, v18, v13
	v_mul_f32_e32 v14, v19, v14
	v_mul_f32_e32 v15, v20, v15
	v_mul_f32_e32 v16, v21, v16
	v_mul_f32_e32 v17, v22, v17
	v_mul_f32_e32 v10, v23, v10
	v_mul_f32_e32 v11, v24, v11
	v_mul_f32_e32 v12, v25, v12
	v_exp_f32_e64 v25, -v13
	v_exp_f32_e64 v18, -v14
	v_exp_f32_e64 v19, -v15
	v_exp_f32_e64 v20, -v16
	v_exp_f32_e64 v21, -v17
	v_exp_f32_e64 v22, -v10
	v_exp_f32_e64 v23, -v11
	v_exp_f32_e64 v24, -v12
	v_add_f32_e32 v25, 1.0, v25
	v_add_f32_e32 v18, 1.0, v18
	v_add_f32_e32 v19, 1.0, v19
	v_add_f32_e32 v20, 1.0, v20
	v_add_f32_e32 v21, 1.0, v21
	v_add_f32_e32 v22, 1.0, v22
	v_add_f32_e32 v23, 1.0, v23
	v_add_f32_e32 v24, 1.0, v24
	v_rcp_f32_e32 v25, v25
	v_rcp_f32_e32 v18, v18
	v_rcp_f32_e32 v19, v19
	v_rcp_f32_e32 v20, v20
	v_rcp_f32_e32 v21, v21
	v_rcp_f32_e32 v22, v22
	v_rcp_f32_e32 v23, v23
	v_rcp_f32_e32 v24, v24
	v_cvt_pk_bf16_f32 v10, v18, v19
	v_cvt_pk_bf16_f32 v11, v20, v21
	v_cvt_pk_bf16_f32 v12, v22, v23
	v_cvt_pk_bf16_f32 v13, v24, v25
	global_store_dwordx4 v[74:75], v[10:13], off offset:1024
	s_nop 1
	v_mov_b32_e32 v10, v204
	v_mul_f32_e32 v14, v61, v10
	v_mul_f32_e32 v11, v64, v10
	v_mul_f32_e32 v12, v65, v10
	v_mul_f32_e32 v13, v60, v10
	v_mul_f32_e32 v15, v62, v10
	v_mul_f32_e32 v16, v63, v10
	v_mul_f32_e32 v17, v58, v10
	v_mul_f32_e32 v10, v59, v10
	v_mul_f32_e32 v5, v10, v5
	v_mul_f32_e32 v6, v11, v6
	v_mul_f32_e32 v7, v12, v7
	v_mul_f32_e32 v8, v13, v8
	v_mul_f32_e32 v9, v14, v9
	v_mul_f32_e32 v2, v15, v2
	v_mul_f32_e32 v3, v16, v3
	v_mul_f32_e32 v4, v17, v4
	v_exp_f32_e64 v17, -v5
	v_exp_f32_e64 v10, -v6
	v_exp_f32_e64 v11, -v7
	v_exp_f32_e64 v12, -v8
	v_exp_f32_e64 v13, -v9
	v_exp_f32_e64 v14, -v2
	v_exp_f32_e64 v15, -v3
	v_exp_f32_e64 v16, -v4
	v_add_f32_e32 v17, 1.0, v17
	v_add_f32_e32 v10, 1.0, v10
	v_add_f32_e32 v11, 1.0, v11
	v_add_f32_e32 v12, 1.0, v12
	v_add_f32_e32 v13, 1.0, v13
	v_add_f32_e32 v14, 1.0, v14
	v_add_f32_e32 v15, 1.0, v15
	v_add_f32_e32 v16, 1.0, v16
	v_rcp_f32_e32 v17, v17
	v_rcp_f32_e32 v10, v10
	v_rcp_f32_e32 v11, v11
	v_rcp_f32_e32 v12, v12
	v_rcp_f32_e32 v13, v13
	v_rcp_f32_e32 v14, v14
	v_rcp_f32_e32 v15, v15
	v_rcp_f32_e32 v16, v16
	v_cvt_pk_bf16_f32 v2, v10, v11
	v_cvt_pk_bf16_f32 v3, v12, v13
	v_cvt_pk_bf16_f32 v4, v14, v15
	v_cvt_pk_bf16_f32 v5, v16, v17
	global_store_dwordx4 v[66:67], v[2:5], off offset:1024
	s_cbranch_vccnz .LBB0_600
	s_andn2_b64 vcc, exec, s[10:11]
	s_cbranch_vccnz .LBB0_599
	s_barrier
	s_branch .LBB0_599
